# GEMM K-loop: priority flips inverted - s_setprio 1 during the load phase (ds_read + DMA issue), 0 during the MFMA block; reset at step end
# baseline (speedup 1.0000x reference)
.LBB0_64:
	s_add_i32 s33, s42, 2
	s_add_u32 s46, s40, 0x80
	s_addc_u32 s43, s41, 0
	s_add_i32 s80, 0, 0x10000
	s_cmp_eq_u32 s84, s42
	s_cselect_b32 s43, s1, s43
	s_cselect_b32 s42, s0, s46
	s_cselect_b32 s47, s75, vcc_hi
	s_cselect_b32 s46, s74, vcc_lo
	s_add_i32 s5, 0, 0x14000
	v_add_u32_e32 v140, s80, v185
	v_add_u32_e32 v166, s5, v185
	ds_read_b128 v[128:131], v140
	ds_read_b128 v[132:135], v140 offset:1024
	ds_read_b128 v[136:139], v140 offset:2048
	ds_read_b128 v[140:143], v140 offset:3072
	ds_read_b128 v[144:147], v166
	ds_read_b128 v[148:151], v166 offset:1024
	ds_read_b128 v[152:155], v166 offset:2048
	ds_read_b128 v[166:169], v166 offset:3072
	v_lshl_add_u64 v[182:183], s[40:41], 0, v[162:163]
	s_add_i32 m0, s28, 0xc000
	ds_read_b128 v[170:173], v188
	ds_read_b128 v[174:177], v188 offset:1024
	ds_read_b128 v[178:181], v188 offset:2048
	ds_read_b128 v[214:217], v188 offset:3072
	ds_read_b128 v[218:221], v188 offset:4096
	ds_read_b128 v[222:225], v188 offset:5120
	ds_read_b128 v[226:229], v188 offset:6144
	ds_read_b128 v[230:233], v188 offset:7168
	global_load_lds_dwordx4 v[182:183], off
	v_lshl_add_u64 v[182:183], s[40:41], 0, v[164:165]
	s_add_i32 m0, s28, 0xe000
	s_nop 0
	global_load_lds_dwordx4 v[182:183], off
	s_waitcnt vmcnt(8)
	s_waitcnt lgkmcnt(0)
	s_barrier
	s_setprio 0
	s_waitcnt lgkmcnt(0)
	v_mfma_f32_16x16x32_bf16 v[124:127], v[128:131], v[170:173], v[124:127]
	v_mfma_f32_16x16x32_bf16 v[120:123], v[136:139], v[170:173], v[120:123]
	v_mfma_f32_16x16x32_bf16 v[108:111], v[128:131], v[178:181], v[108:111]
	v_mfma_f32_16x16x32_bf16 v[104:107], v[136:139], v[178:181], v[104:107]
	v_mfma_f32_16x16x32_bf16 v[92:95], v[128:131], v[218:221], v[92:95]
	v_mfma_f32_16x16x32_bf16 v[88:91], v[136:139], v[218:221], v[88:91]
	v_mfma_f32_16x16x32_bf16 v[76:79], v[128:131], v[226:229], v[76:79]
	v_mfma_f32_16x16x32_bf16 v[72:75], v[136:139], v[226:229], v[72:75]
	v_mfma_f32_16x16x32_bf16 v[124:127], v[132:135], v[174:177], v[124:127]
	v_mfma_f32_16x16x32_bf16 v[120:123], v[140:143], v[174:177], v[120:123]
	v_mfma_f32_16x16x32_bf16 v[108:111], v[132:135], v[214:217], v[108:111]
	v_mfma_f32_16x16x32_bf16 v[104:107], v[140:143], v[214:217], v[104:107]
	v_mfma_f32_16x16x32_bf16 v[92:95], v[132:135], v[222:225], v[92:95]
	v_mfma_f32_16x16x32_bf16 v[88:91], v[140:143], v[222:225], v[88:91]
	v_mfma_f32_16x16x32_bf16 v[76:79], v[132:135], v[230:233], v[76:79]
	v_mfma_f32_16x16x32_bf16 v[72:75], v[140:143], v[230:233], v[72:75]
	v_mfma_f32_16x16x32_bf16 v[116:119], v[144:147], v[170:173], v[116:119]
	v_mfma_f32_16x16x32_bf16 v[112:115], v[152:155], v[170:173], v[112:115]
	v_mfma_f32_16x16x32_bf16 v[100:103], v[144:147], v[178:181], v[100:103]
	v_mfma_f32_16x16x32_bf16 v[96:99], v[152:155], v[178:181], v[96:99]
	v_mfma_f32_16x16x32_bf16 v[84:87], v[144:147], v[218:221], v[84:87]
	v_mfma_f32_16x16x32_bf16 v[80:83], v[152:155], v[218:221], v[80:83]
	v_mfma_f32_16x16x32_bf16 v[68:71], v[144:147], v[226:229], v[68:71]
	v_mfma_f32_16x16x32_bf16 v[64:67], v[152:155], v[226:229], v[64:67]
	v_mfma_f32_16x16x32_bf16 v[116:119], v[148:151], v[174:177], v[116:119]
	v_mfma_f32_16x16x32_bf16 v[112:115], v[166:169], v[174:177], v[112:115]
	v_mfma_f32_16x16x32_bf16 v[100:103], v[148:151], v[214:217], v[100:103]
	v_mfma_f32_16x16x32_bf16 v[96:99], v[166:169], v[214:217], v[96:99]
	v_mfma_f32_16x16x32_bf16 v[84:87], v[148:151], v[222:225], v[84:87]
	v_mfma_f32_16x16x32_bf16 v[80:83], v[166:169], v[222:225], v[80:83]
	v_mfma_f32_16x16x32_bf16 v[68:71], v[148:151], v[230:233], v[68:71]
	v_mfma_f32_16x16x32_bf16 v[64:67], v[166:169], v[230:233], v[64:67]
	s_setprio 1
	s_barrier
	s_add_i32 s80, s80, s27
	v_lshl_add_u64 v[182:183], s[46:47], 0, v[192:193]
	s_mov_b32 m0, s80
	ds_read_b128 v[170:173], v188 offset:16384
	ds_read_b128 v[174:177], v188 offset:17408
	ds_read_b128 v[178:181], v188 offset:18432
	ds_read_b128 v[214:217], v188 offset:19456
	ds_read_b128 v[218:221], v188 offset:20480
	ds_read_b128 v[222:225], v188 offset:21504
	ds_read_b128 v[226:229], v188 offset:22528
	ds_read_b128 v[230:233], v188 offset:23552
	global_load_lds_dwordx4 v[182:183], off
	s_add_i32 m0, s80, 0x2000
	v_lshl_add_u64 v[190:191], s[46:47], 0, v[160:161]
	s_add_u32 s46, s46, s30
	s_addc_u32 s47, s47, 0
	s_add_i32 s5, s5, s27
	global_load_lds_dwordx4 v[190:191], off
	v_lshl_add_u64 v[200:201], s[46:47], 0, v[192:193]
	s_mov_b32 m0, s5
	v_lshl_add_u64 v[234:235], s[46:47], 0, v[160:161]
	global_load_lds_dwordx4 v[200:201], off
	s_add_i32 m0, s5, 0x2000
	v_lshl_add_u64 v[236:237], s[42:43], 0, v[156:157]
	global_load_lds_dwordx4 v[234:235], off
	s_mov_b32 m0, s28
	v_lshl_add_u64 v[238:239], s[42:43], 0, v[158:159]
	global_load_lds_dwordx4 v[236:237], off
	s_mov_b32 m0, s69
	s_nop 0
	global_load_lds_dwordx4 v[238:239], off
	s_waitcnt vmcnt(8)
	s_waitcnt lgkmcnt(0)
	s_barrier
	s_setprio 0
	s_waitcnt lgkmcnt(0)
	v_mfma_f32_16x16x32_bf16 v[60:63], v[128:131], v[170:173], v[60:63]
	v_mfma_f32_16x16x32_bf16 v[56:59], v[136:139], v[170:173], v[56:59]
	v_mfma_f32_16x16x32_bf16 v[44:47], v[128:131], v[178:181], v[44:47]
	v_mfma_f32_16x16x32_bf16 v[40:43], v[136:139], v[178:181], v[40:43]
	v_mfma_f32_16x16x32_bf16 v[28:31], v[128:131], v[218:221], v[28:31]
	v_mfma_f32_16x16x32_bf16 v[24:27], v[136:139], v[218:221], v[24:27]
	v_mfma_f32_16x16x32_bf16 v[12:15], v[128:131], v[226:229], v[12:15]
	v_mfma_f32_16x16x32_bf16 v[8:11], v[136:139], v[226:229], v[8:11]
	v_mfma_f32_16x16x32_bf16 v[60:63], v[132:135], v[174:177], v[60:63]
	v_mfma_f32_16x16x32_bf16 v[56:59], v[140:143], v[174:177], v[56:59]
	v_mfma_f32_16x16x32_bf16 v[44:47], v[132:135], v[214:217], v[44:47]
	v_mfma_f32_16x16x32_bf16 v[40:43], v[140:143], v[214:217], v[40:43]
	v_mfma_f32_16x16x32_bf16 v[28:31], v[132:135], v[222:225], v[28:31]
	v_mfma_f32_16x16x32_bf16 v[24:27], v[140:143], v[222:225], v[24:27]
	v_mfma_f32_16x16x32_bf16 v[12:15], v[132:135], v[230:233], v[12:15]
	v_mfma_f32_16x16x32_bf16 v[8:11], v[140:143], v[230:233], v[8:11]
	v_mfma_f32_16x16x32_bf16 v[52:55], v[144:147], v[170:173], v[52:55]
	v_mfma_f32_16x16x32_bf16 v[48:51], v[152:155], v[170:173], v[48:51]
	v_mfma_f32_16x16x32_bf16 v[36:39], v[144:147], v[178:181], v[36:39]
	v_mfma_f32_16x16x32_bf16 v[32:35], v[152:155], v[178:181], v[32:35]
	v_mfma_f32_16x16x32_bf16 v[20:23], v[144:147], v[218:221], v[20:23]
	v_mfma_f32_16x16x32_bf16 v[16:19], v[152:155], v[218:221], v[16:19]
	v_mfma_f32_16x16x32_bf16 v[4:7], v[144:147], v[226:229], v[4:7]
	v_mfma_f32_16x16x32_bf16 v[0:3], v[152:155], v[226:229], v[0:3]
	v_mfma_f32_16x16x32_bf16 v[52:55], v[148:151], v[174:177], v[52:55]
	v_mfma_f32_16x16x32_bf16 v[48:51], v[166:169], v[174:177], v[48:51]
	v_mfma_f32_16x16x32_bf16 v[36:39], v[148:151], v[214:217], v[36:39]
	v_mfma_f32_16x16x32_bf16 v[32:35], v[166:169], v[214:217], v[32:35]
	v_mfma_f32_16x16x32_bf16 v[20:23], v[148:151], v[222:225], v[20:23]
	v_mfma_f32_16x16x32_bf16 v[16:19], v[166:169], v[222:225], v[16:19]
	v_mfma_f32_16x16x32_bf16 v[4:7], v[148:151], v[230:233], v[4:7]
	v_mfma_f32_16x16x32_bf16 v[0:3], v[166:169], v[230:233], v[0:3]
	s_setprio 1
	s_barrier
.Lmy_sp3:
	s_add_i32 s5, 0, 0x18000
	s_add_i32 s46, 0, 0x1c000
	v_add_u32_e32 v140, s5, v185
	v_add_u32_e32 v166, s46, v185
	ds_read_b128 v[128:131], v140
	ds_read_b128 v[132:135], v140 offset:1024
	ds_read_b128 v[136:139], v140 offset:2048
	ds_read_b128 v[140:143], v140 offset:3072
	ds_read_b128 v[144:147], v166
	ds_read_b128 v[148:151], v166 offset:1024
	ds_read_b128 v[152:155], v166 offset:2048
	ds_read_b128 v[166:169], v166 offset:3072
	s_add_u32 s42, s42, s30
	s_addc_u32 s43, s43, 0
	s_mov_b32 m0, s72
	v_lshl_add_u64 v[240:241], s[42:43], 0, v[156:157]
	ds_read_b128 v[170:173], v188 offset:32768
	ds_read_b128 v[174:177], v188 offset:33792
	ds_read_b128 v[178:181], v188 offset:34816
	ds_read_b128 v[214:217], v188 offset:35840
	ds_read_b128 v[218:221], v188 offset:36864
	ds_read_b128 v[222:225], v188 offset:37888
	ds_read_b128 v[226:229], v188 offset:38912
	ds_read_b128 v[230:233], v188 offset:39936
	global_load_lds_dwordx4 v[240:241], off
	v_lshl_add_u64 v[240:241], s[42:43], 0, v[158:159]
	s_mov_b32 m0, s76
	s_nop 0
	global_load_lds_dwordx4 v[240:241], off
	s_waitcnt vmcnt(8)
	s_waitcnt lgkmcnt(0)
	s_barrier
	s_setprio 0
	s_waitcnt lgkmcnt(0)
	v_mfma_f32_16x16x32_bf16 v[124:127], v[128:131], v[170:173], v[124:127]
	v_mfma_f32_16x16x32_bf16 v[120:123], v[136:139], v[170:173], v[120:123]
	v_mfma_f32_16x16x32_bf16 v[108:111], v[128:131], v[178:181], v[108:111]
	v_mfma_f32_16x16x32_bf16 v[104:107], v[136:139], v[178:181], v[104:107]
	v_mfma_f32_16x16x32_bf16 v[92:95], v[128:131], v[218:221], v[92:95]
	v_mfma_f32_16x16x32_bf16 v[88:91], v[136:139], v[218:221], v[88:91]
	v_mfma_f32_16x16x32_bf16 v[76:79], v[128:131], v[226:229], v[76:79]
	v_mfma_f32_16x16x32_bf16 v[72:75], v[136:139], v[226:229], v[72:75]
	v_mfma_f32_16x16x32_bf16 v[124:127], v[132:135], v[174:177], v[124:127]
	v_mfma_f32_16x16x32_bf16 v[120:123], v[140:143], v[174:177], v[120:123]
	v_mfma_f32_16x16x32_bf16 v[108:111], v[132:135], v[214:217], v[108:111]
	v_mfma_f32_16x16x32_bf16 v[104:107], v[140:143], v[214:217], v[104:107]
	v_mfma_f32_16x16x32_bf16 v[92:95], v[132:135], v[222:225], v[92:95]
	v_mfma_f32_16x16x32_bf16 v[88:91], v[140:143], v[222:225], v[88:91]
	v_mfma_f32_16x16x32_bf16 v[76:79], v[132:135], v[230:233], v[76:79]
	v_mfma_f32_16x16x32_bf16 v[72:75], v[140:143], v[230:233], v[72:75]
	v_mfma_f32_16x16x32_bf16 v[116:119], v[144:147], v[170:173], v[116:119]
	v_mfma_f32_16x16x32_bf16 v[112:115], v[152:155], v[170:173], v[112:115]
	v_mfma_f32_16x16x32_bf16 v[100:103], v[144:147], v[178:181], v[100:103]
	v_mfma_f32_16x16x32_bf16 v[96:99], v[152:155], v[178:181], v[96:99]
	v_mfma_f32_16x16x32_bf16 v[84:87], v[144:147], v[218:221], v[84:87]
	v_mfma_f32_16x16x32_bf16 v[80:83], v[152:155], v[218:221], v[80:83]
	v_mfma_f32_16x16x32_bf16 v[68:71], v[144:147], v[226:229], v[68:71]
	v_mfma_f32_16x16x32_bf16 v[64:67], v[152:155], v[226:229], v[64:67]
	v_mfma_f32_16x16x32_bf16 v[116:119], v[148:151], v[174:177], v[116:119]
	v_mfma_f32_16x16x32_bf16 v[112:115], v[166:169], v[174:177], v[112:115]
	v_mfma_f32_16x16x32_bf16 v[100:103], v[148:151], v[214:217], v[100:103]
	v_mfma_f32_16x16x32_bf16 v[96:99], v[166:169], v[214:217], v[96:99]
	v_mfma_f32_16x16x32_bf16 v[84:87], v[148:151], v[222:225], v[84:87]
	v_mfma_f32_16x16x32_bf16 v[80:83], v[166:169], v[222:225], v[80:83]
	v_mfma_f32_16x16x32_bf16 v[68:71], v[148:151], v[230:233], v[68:71]
	v_mfma_f32_16x16x32_bf16 v[64:67], v[166:169], v[230:233], v[64:67]
	s_setprio 1
	s_barrier
	s_add_i32 s5, s5, s27
	v_lshl_add_u64 v[182:183], v[182:183], 0, s[70:71]
	s_mov_b32 m0, s5
	ds_read_b128 v[170:173], v188 offset:49152
	ds_read_b128 v[174:177], v188 offset:50176
	ds_read_b128 v[178:181], v188 offset:51200
	ds_read_b128 v[214:217], v188 offset:52224
	ds_read_b128 v[218:221], v188 offset:53248
	ds_read_b128 v[222:225], v188 offset:54272
	ds_read_b128 v[226:229], v188 offset:55296
	ds_read_b128 v[230:233], v188 offset:56320
	global_load_lds_dwordx4 v[182:183], off
	v_lshl_add_u64 v[182:183], v[190:191], 0, s[70:71]
	s_add_i32 m0, s5, 0x2000
	s_add_i32 s5, s46, s27
	global_load_lds_dwordx4 v[182:183], off
	v_lshl_add_u64 v[182:183], v[200:201], 0, s[70:71]
	s_mov_b32 m0, s5
	s_nop 0
	global_load_lds_dwordx4 v[182:183], off
	v_lshl_add_u64 v[182:183], v[234:235], 0, s[70:71]
	s_add_i32 m0, s5, 0x2000
	s_nop 0
	global_load_lds_dwordx4 v[182:183], off
	v_lshl_add_u64 v[182:183], v[236:237], 0, s[70:71]
	s_mov_b32 m0, s81
	s_nop 0
	global_load_lds_dwordx4 v[182:183], off
	v_lshl_add_u64 v[182:183], v[238:239], 0, s[70:71]
	s_mov_b32 m0, s82
	s_nop 0
	global_load_lds_dwordx4 v[182:183], off
	s_waitcnt vmcnt(8)
	s_waitcnt lgkmcnt(0)
	s_barrier
	s_setprio 0
	s_waitcnt lgkmcnt(0)
	v_mfma_f32_16x16x32_bf16 v[60:63], v[128:131], v[170:173], v[60:63]
	v_mfma_f32_16x16x32_bf16 v[56:59], v[136:139], v[170:173], v[56:59]
	v_mfma_f32_16x16x32_bf16 v[44:47], v[128:131], v[178:181], v[44:47]
	v_mfma_f32_16x16x32_bf16 v[40:43], v[136:139], v[178:181], v[40:43]
	v_mfma_f32_16x16x32_bf16 v[28:31], v[128:131], v[218:221], v[28:31]
	v_mfma_f32_16x16x32_bf16 v[24:27], v[136:139], v[218:221], v[24:27]
	v_mfma_f32_16x16x32_bf16 v[12:15], v[128:131], v[226:229], v[12:15]
	v_mfma_f32_16x16x32_bf16 v[8:11], v[136:139], v[226:229], v[8:11]
	v_mfma_f32_16x16x32_bf16 v[60:63], v[132:135], v[174:177], v[60:63]
	v_mfma_f32_16x16x32_bf16 v[56:59], v[140:143], v[174:177], v[56:59]
	v_mfma_f32_16x16x32_bf16 v[44:47], v[132:135], v[214:217], v[44:47]
	v_mfma_f32_16x16x32_bf16 v[40:43], v[140:143], v[214:217], v[40:43]
	v_mfma_f32_16x16x32_bf16 v[28:31], v[132:135], v[222:225], v[28:31]
	v_mfma_f32_16x16x32_bf16 v[24:27], v[140:143], v[222:225], v[24:27]
	v_mfma_f32_16x16x32_bf16 v[12:15], v[132:135], v[230:233], v[12:15]
	v_mfma_f32_16x16x32_bf16 v[8:11], v[140:143], v[230:233], v[8:11]
	v_mfma_f32_16x16x32_bf16 v[52:55], v[144:147], v[170:173], v[52:55]
	v_mfma_f32_16x16x32_bf16 v[48:51], v[152:155], v[170:173], v[48:51]
	v_mfma_f32_16x16x32_bf16 v[36:39], v[144:147], v[178:181], v[36:39]
	v_mfma_f32_16x16x32_bf16 v[32:35], v[152:155], v[178:181], v[32:35]
	v_mfma_f32_16x16x32_bf16 v[20:23], v[144:147], v[218:221], v[20:23]
	v_mfma_f32_16x16x32_bf16 v[16:19], v[152:155], v[218:221], v[16:19]
	v_mfma_f32_16x16x32_bf16 v[4:7], v[144:147], v[226:229], v[4:7]
	v_mfma_f32_16x16x32_bf16 v[0:3], v[152:155], v[226:229], v[0:3]
	v_mfma_f32_16x16x32_bf16 v[52:55], v[148:151], v[174:177], v[52:55]
	v_mfma_f32_16x16x32_bf16 v[48:51], v[166:169], v[174:177], v[48:51]
	v_mfma_f32_16x16x32_bf16 v[36:39], v[148:151], v[214:217], v[36:39]
	v_mfma_f32_16x16x32_bf16 v[32:35], v[166:169], v[214:217], v[32:35]
	v_mfma_f32_16x16x32_bf16 v[20:23], v[148:151], v[222:225], v[20:23]
	v_mfma_f32_16x16x32_bf16 v[16:19], v[166:169], v[222:225], v[16:19]
	v_mfma_f32_16x16x32_bf16 v[4:7], v[148:151], v[230:233], v[4:7]
	v_mfma_f32_16x16x32_bf16 v[0:3], v[166:169], v[230:233], v[0:3]
	s_setprio 1
	s_barrier
	s_add_u32 s40, s40, 0x100
	s_addc_u32 s41, s41, 0
	s_add_u32 vcc_lo, vcc_lo, 0x100
	s_addc_u32 vcc_hi, vcc_hi, 0
	s_cmp_ge_u32 s33, s78
	s_mov_b32 s42, s33
	s_cbranch_scc0 .LBB0_64
	s_and_b64 vcc, exec, s[66:67]
	s_cbranch_vccz .LBB0_67
	s_barrier

.Lmy_peel:
	s_add_i32 s33, s42, 2
	s_add_u32 s46, s40, 0x80
	s_addc_u32 s43, s41, 0
	s_add_i32 s80, 0, 0x10000
	s_cmp_eq_u32 s84, s42
	s_cselect_b32 s43, s1, s43
	s_cselect_b32 s42, s0, s46
	s_cselect_b32 s47, s75, vcc_hi
	s_cselect_b32 s46, s74, vcc_lo
	s_add_i32 s5, 0, 0x14000
	v_add_u32_e32 v140, s80, v185
	v_add_u32_e32 v166, s5, v185
	ds_read_b128 v[128:131], v140
	ds_read_b128 v[132:135], v140 offset:1024
	ds_read_b128 v[136:139], v140 offset:2048
	ds_read_b128 v[140:143], v140 offset:3072
	ds_read_b128 v[144:147], v166
	ds_read_b128 v[148:151], v166 offset:1024
	ds_read_b128 v[152:155], v166 offset:2048
	ds_read_b128 v[166:169], v166 offset:3072
	v_lshl_add_u64 v[182:183], s[40:41], 0, v[162:163]
	s_add_i32 m0, s28, 0xc000
	ds_read_b128 v[170:173], v188
	ds_read_b128 v[174:177], v188 offset:1024
	ds_read_b128 v[178:181], v188 offset:2048
	ds_read_b128 v[214:217], v188 offset:3072
	ds_read_b128 v[218:221], v188 offset:4096
	ds_read_b128 v[222:225], v188 offset:5120
	ds_read_b128 v[226:229], v188 offset:6144
	ds_read_b128 v[230:233], v188 offset:7168
	global_load_lds_dwordx4 v[182:183], off
	v_lshl_add_u64 v[182:183], s[40:41], 0, v[164:165]
	s_add_i32 m0, s28, 0xe000
	s_nop 0
	global_load_lds_dwordx4 v[182:183], off
	s_waitcnt vmcnt(24)
	s_waitcnt lgkmcnt(0)
	s_barrier
	s_setprio 0
	s_waitcnt lgkmcnt(0)
	v_mfma_f32_16x16x32_bf16 v[124:127], v[128:131], v[170:173], 0
	v_mfma_f32_16x16x32_bf16 v[120:123], v[136:139], v[170:173], 0
	v_mfma_f32_16x16x32_bf16 v[108:111], v[128:131], v[178:181], 0
	v_mfma_f32_16x16x32_bf16 v[104:107], v[136:139], v[178:181], 0
	v_mfma_f32_16x16x32_bf16 v[92:95], v[128:131], v[218:221], 0
	v_mfma_f32_16x16x32_bf16 v[88:91], v[136:139], v[218:221], 0
	v_mfma_f32_16x16x32_bf16 v[76:79], v[128:131], v[226:229], 0
	v_mfma_f32_16x16x32_bf16 v[72:75], v[136:139], v[226:229], 0
	v_mfma_f32_16x16x32_bf16 v[124:127], v[132:135], v[174:177], v[124:127]
	v_mfma_f32_16x16x32_bf16 v[120:123], v[140:143], v[174:177], v[120:123]
	v_mfma_f32_16x16x32_bf16 v[108:111], v[132:135], v[214:217], v[108:111]
	v_mfma_f32_16x16x32_bf16 v[104:107], v[140:143], v[214:217], v[104:107]
	v_mfma_f32_16x16x32_bf16 v[92:95], v[132:135], v[222:225], v[92:95]
	v_mfma_f32_16x16x32_bf16 v[88:91], v[140:143], v[222:225], v[88:91]
	v_mfma_f32_16x16x32_bf16 v[76:79], v[132:135], v[230:233], v[76:79]
	v_mfma_f32_16x16x32_bf16 v[72:75], v[140:143], v[230:233], v[72:75]
	v_mfma_f32_16x16x32_bf16 v[116:119], v[144:147], v[170:173], 0
	v_mfma_f32_16x16x32_bf16 v[112:115], v[152:155], v[170:173], 0
	v_mfma_f32_16x16x32_bf16 v[100:103], v[144:147], v[178:181], 0
	v_mfma_f32_16x16x32_bf16 v[96:99], v[152:155], v[178:181], 0
	v_mfma_f32_16x16x32_bf16 v[84:87], v[144:147], v[218:221], 0
	v_mfma_f32_16x16x32_bf16 v[80:83], v[152:155], v[218:221], 0
	v_mfma_f32_16x16x32_bf16 v[68:71], v[144:147], v[226:229], 0
	v_mfma_f32_16x16x32_bf16 v[64:67], v[152:155], v[226:229], 0
	v_mfma_f32_16x16x32_bf16 v[116:119], v[148:151], v[174:177], v[116:119]
	v_mfma_f32_16x16x32_bf16 v[112:115], v[166:169], v[174:177], v[112:115]
	v_mfma_f32_16x16x32_bf16 v[100:103], v[148:151], v[214:217], v[100:103]
	v_mfma_f32_16x16x32_bf16 v[96:99], v[166:169], v[214:217], v[96:99]
	v_mfma_f32_16x16x32_bf16 v[84:87], v[148:151], v[222:225], v[84:87]
	v_mfma_f32_16x16x32_bf16 v[80:83], v[166:169], v[222:225], v[80:83]
	v_mfma_f32_16x16x32_bf16 v[68:71], v[148:151], v[230:233], v[68:71]
	v_mfma_f32_16x16x32_bf16 v[64:67], v[166:169], v[230:233], v[64:67]
	s_setprio 1
	s_barrier
	s_add_i32 s80, s80, s27
	v_lshl_add_u64 v[182:183], s[46:47], 0, v[192:193]
	s_mov_b32 m0, s80
	ds_read_b128 v[170:173], v188 offset:16384
	ds_read_b128 v[174:177], v188 offset:17408
	ds_read_b128 v[178:181], v188 offset:18432
	ds_read_b128 v[214:217], v188 offset:19456
	ds_read_b128 v[218:221], v188 offset:20480
	ds_read_b128 v[222:225], v188 offset:21504
	ds_read_b128 v[226:229], v188 offset:22528
	ds_read_b128 v[230:233], v188 offset:23552
	global_load_lds_dwordx4 v[182:183], off
	s_add_i32 m0, s80, 0x2000
	v_lshl_add_u64 v[190:191], s[46:47], 0, v[160:161]
	s_add_u32 s46, s46, s30
	s_addc_u32 s47, s47, 0
	s_add_i32 s5, s5, s27
	global_load_lds_dwordx4 v[190:191], off
	v_lshl_add_u64 v[200:201], s[46:47], 0, v[192:193]
	s_mov_b32 m0, s5
	v_lshl_add_u64 v[234:235], s[46:47], 0, v[160:161]
	global_load_lds_dwordx4 v[200:201], off
	s_add_i32 m0, s5, 0x2000
	v_lshl_add_u64 v[236:237], s[42:43], 0, v[156:157]
	global_load_lds_dwordx4 v[234:235], off
	s_mov_b32 m0, s28
	v_lshl_add_u64 v[238:239], s[42:43], 0, v[158:159]
	global_load_lds_dwordx4 v[236:237], off
	s_mov_b32 m0, s69
	s_nop 0
	global_load_lds_dwordx4 v[238:239], off
	s_waitcnt vmcnt(24)
	s_waitcnt lgkmcnt(0)
	s_barrier
	s_setprio 0
	s_waitcnt lgkmcnt(0)
	v_mfma_f32_16x16x32_bf16 v[60:63], v[128:131], v[170:173], 0
	v_mfma_f32_16x16x32_bf16 v[56:59], v[136:139], v[170:173], 0
	v_mfma_f32_16x16x32_bf16 v[44:47], v[128:131], v[178:181], 0
	v_mfma_f32_16x16x32_bf16 v[40:43], v[136:139], v[178:181], 0
	v_mfma_f32_16x16x32_bf16 v[28:31], v[128:131], v[218:221], 0
	v_mfma_f32_16x16x32_bf16 v[24:27], v[136:139], v[218:221], 0
	v_mfma_f32_16x16x32_bf16 v[12:15], v[128:131], v[226:229], 0
	v_mfma_f32_16x16x32_bf16 v[8:11], v[136:139], v[226:229], 0
	v_mfma_f32_16x16x32_bf16 v[60:63], v[132:135], v[174:177], v[60:63]
	v_mfma_f32_16x16x32_bf16 v[56:59], v[140:143], v[174:177], v[56:59]
	v_mfma_f32_16x16x32_bf16 v[44:47], v[132:135], v[214:217], v[44:47]
	v_mfma_f32_16x16x32_bf16 v[40:43], v[140:143], v[214:217], v[40:43]
	v_mfma_f32_16x16x32_bf16 v[28:31], v[132:135], v[222:225], v[28:31]
	v_mfma_f32_16x16x32_bf16 v[24:27], v[140:143], v[222:225], v[24:27]
	v_mfma_f32_16x16x32_bf16 v[12:15], v[132:135], v[230:233], v[12:15]
	v_mfma_f32_16x16x32_bf16 v[8:11], v[140:143], v[230:233], v[8:11]
	v_mfma_f32_16x16x32_bf16 v[52:55], v[144:147], v[170:173], 0
	v_mfma_f32_16x16x32_bf16 v[48:51], v[152:155], v[170:173], 0
	v_mfma_f32_16x16x32_bf16 v[36:39], v[144:147], v[178:181], 0
	v_mfma_f32_16x16x32_bf16 v[32:35], v[152:155], v[178:181], 0
	v_mfma_f32_16x16x32_bf16 v[20:23], v[144:147], v[218:221], 0
	v_mfma_f32_16x16x32_bf16 v[16:19], v[152:155], v[218:221], 0
	v_mfma_f32_16x16x32_bf16 v[4:7], v[144:147], v[226:229], 0
	v_mfma_f32_16x16x32_bf16 v[0:3], v[152:155], v[226:229], 0
	v_mfma_f32_16x16x32_bf16 v[52:55], v[148:151], v[174:177], v[52:55]
	v_mfma_f32_16x16x32_bf16 v[48:51], v[166:169], v[174:177], v[48:51]
	v_mfma_f32_16x16x32_bf16 v[36:39], v[148:151], v[214:217], v[36:39]
	v_mfma_f32_16x16x32_bf16 v[32:35], v[166:169], v[214:217], v[32:35]
	v_mfma_f32_16x16x32_bf16 v[20:23], v[148:151], v[222:225], v[20:23]
	v_mfma_f32_16x16x32_bf16 v[16:19], v[166:169], v[222:225], v[16:19]
	v_mfma_f32_16x16x32_bf16 v[4:7], v[148:151], v[230:233], v[4:7]
	v_mfma_f32_16x16x32_bf16 v[0:3], v[166:169], v[230:233], v[0:3]
	s_setprio 1
	s_barrier
	s_branch .Lmy_sp3
